# top-counter polling barrier + XCD leader invalidates its L1 together with its arrival atomic (first release poll not queued behind the invalidate)
# baseline (speedup 1.0000x reference)
.LBB0_1149:
	s_or_b64 exec, exec, s[8:9]
	s_waitcnt vmcnt(0)
	v_readfirstlane_b32 s6, v3
	v_sub_u32_e32 v4, 0, v2
	s_mov_b64 s[10:11], 0
	v_add_u32_e32 v3, s6, v0
	v_cvt_f32_u32_e32 v0, v2
	s_add_u32 s6, s2, 0x83400
	s_addc_u32 s7, s3, 0
	v_rcp_iflag_f32_e32 v0, v0
	s_nop 0
	v_mul_f32_e32 v0, 0x4f7ffffe, v0
	v_cvt_u32_f32_e32 v0, v0
	v_mul_lo_u32 v4, v4, v0
	v_mul_hi_u32 v4, v0, v4
	v_add_u32_e32 v0, v0, v4
	v_mul_hi_u32 v0, v3, v0
	v_mul_lo_u32 v4, v0, v2
	v_sub_u32_e32 v4, v3, v4
	v_cmp_ge_u32_e32 vcc, v4, v2
	v_add_u32_e32 v5, 1, v0
	v_add_u32_e32 v3, 1, v3
	v_cndmask_b32_e32 v0, v0, v5, vcc
	v_sub_u32_e32 v5, v4, v2
	v_cndmask_b32_e32 v4, v4, v5, vcc
	v_cmp_ge_u32_e32 vcc, v4, v2
	v_add_u32_e32 v4, 1, v0
	s_nop 0
	v_cndmask_b32_e32 v0, v0, v4, vcc
	v_mul_lo_u32 v4, v2, v0
	v_add_u32_e32 v2, v4, v2
	v_mov_b32_e32 v4, v2
	v_cmp_ne_u32_e32 vcc, v3, v2
	v_mov_b64_e32 v[2:3], s[6:7]
	s_and_saveexec_b64 s[8:9], vcc
	s_cbranch_execz .LBB0_1161
	global_load_dword v2, v1, s[6:7] sc1
	s_mov_b64 s[14:15], 0
	s_waitcnt vmcnt(0)
	v_cmp_lt_u32_e32 vcc, v2, v4
	s_and_saveexec_b64 s[12:13], vcc
	s_cbranch_execz .LBB0_1160
	s_add_u32 s10, s2, 0x80200
	s_addc_u32 s11, s3, 0
	s_mov_b32 s22, 1
	s_mov_b64 s[2:3], 0
	s_branch .LBB0_1153
